# ssm_pass1 block fronts hand-written too (MFMA->LDS transpose->scalar scan with hbuf stores); hipcc tails kept
# speedup vs baseline: 1.0128x; 1.0020x over previous
.LBB0_915:
	s_add_i32 s36, s34, 4
	s_min_i32 s2, s36, 0x80
	s_lshl_b32 s2, s2, 4
	s_add_i32 s2, s2, s30
	s_cmp_lg_u32 s34, -4
	s_cselect_b32 s2, s2, 0x8000
	v_or_b32_e32 v20, s2, v121
	s_add_i32 s2, s34, 5
	s_min_i32 s2, s2, 0x80
	s_lshl_b32 s2, s2, 4
	s_add_i32 s2, s2, s30
	v_ashrrev_i32_e32 v21, 31, v20
	s_cmp_lg_u32 s34, -5
	v_lshlrev_b64 v[20:21], 10, v[20:21]
	s_cselect_b32 s2, s2, 0x8000
	v_lshl_add_u64 v[80:81], v[24:25], 0, v[20:21]
	v_or_b32_e32 v20, s2, v121
	s_add_i32 s2, s34, 6
	s_min_i32 s2, s2, 0x80
	s_lshl_b32 s2, s2, 4
	s_add_i32 s2, s2, s30
	v_ashrrev_i32_e32 v21, 31, v20
	s_cmp_lg_u32 s34, -6
	v_lshlrev_b64 v[20:21], 10, v[20:21]
	s_cselect_b32 s2, s2, 0x8000
	v_lshl_add_u64 v[82:83], v[24:25], 0, v[20:21]
	v_or_b32_e32 v20, s2, v121
	s_add_i32 s2, s34, 7
	s_min_i32 s2, s2, 0x80
	s_lshl_b32 s2, s2, 4
	s_add_i32 s2, s2, s30
	s_cmp_lg_u32 s34, -7
	s_cselect_b32 s2, s2, 0x8000
	v_or_b32_e32 v84, s2, v121
	v_ashrrev_i32_e32 v21, 31, v20
	v_ashrrev_i32_e32 v85, 31, v84
	v_lshlrev_b64 v[20:21], 10, v[20:21]
	v_lshlrev_b64 v[84:85], 10, v[84:85]
	v_lshl_add_u64 v[116:117], v[24:25], 0, v[20:21]
	v_lshl_add_u64 v[118:119], v[24:25], 0, v[84:85]
	global_load_dwordx2 v[86:87], v[80:81], off
	global_load_dwordx2 v[84:85], v[82:83], off
	global_load_dwordx2 v[82:83], v[116:117], off
	global_load_dwordx2 v[80:81], v[118:119], off
	s_waitcnt vmcnt(4)
	v_mfma_f32_16x16x16_bf16 v[204:207], v[28:29], v[92:93], 0
	v_mfma_f32_16x16x16_bf16 v[208:211], v[30:31], v[92:93], 0
	v_mfma_f32_16x16x16_bf16 v[212:215], v[66:67], v[92:93], 0
	v_mfma_f32_16x16x16_bf16 v[216:219], v[68:69], v[92:93], 0
	v_mfma_f32_16x16x16_bf16 v[220:223], v[70:71], v[92:93], 0
	v_mfma_f32_16x16x16_bf16 v[224:227], v[72:73], v[92:93], 0
	v_mfma_f32_16x16x16_bf16 v[228:231], v[74:75], v[92:93], 0
	v_mfma_f32_16x16x16_bf16 v[232:235], v[76:77], v[92:93], 0
	s_nop 7
	ds_write2_b32 v96, v204, v208 offset1:16
	ds_write2_b32 v96, v205, v209 offset0:36 offset1:52
	ds_write2_b32 v96, v206, v210 offset0:72 offset1:88
	ds_write2_b32 v96, v207, v211 offset0:108 offset1:124
	ds_write2_b32 v100, v212, v216 offset0:64 offset1:80
	ds_write2_b32 v100, v213, v217 offset0:100 offset1:116
	ds_write2_b32 v100, v214, v218 offset0:136 offset1:152
	ds_write2_b32 v100, v215, v219 offset0:172 offset1:188
	ds_write2_b32 v101, v220, v224 offset0:128 offset1:144
	ds_write2_b32 v101, v221, v225 offset0:164 offset1:180
	ds_write2_b32 v101, v222, v226 offset0:200 offset1:216
	ds_write2_b32 v101, v223, v227 offset0:236 offset1:252
	ds_write2_b32 v102, v228, v232 offset0:192 offset1:208
	ds_write2_b32 v102, v229, v233 offset0:228 offset1:244
	ds_write2_b32 v103, v230, v234 offset0:8 offset1:24
	ds_write2_b32 v103, v231, v235 offset0:44 offset1:60
	s_waitcnt lgkmcnt(0)
	ds_read_b128 v[236:239], v49
	ds_read_b128 v[240:243], v49 offset:16
	ds_read_b128 v[244:247], v49 offset:32
	ds_read_b128 v[248:251], v49 offset:48
	ds_read_b128 v[158:161], v49 offset:64
	ds_read_b128 v[162:165], v49 offset:80
	ds_read_b128 v[166:169], v49 offset:96
	ds_read_b128 v[170:173], v49 offset:112
	s_waitcnt lgkmcnt(3)
	v_mul_f32_e32 v252, v60, v65
	v_mul_f32_e32 v253, v60, v64
	v_fma_f32 v252, v62, v64, -v252
	v_fma_f32 v253, v62, v65, v253
	v_add_f32_e32 v64, v236, v252
	v_add_f32_e32 v65, v158, v253
	v_cvt_pk_bf16_f32 v202, v64, v65
	ds_write_b32 v104, v202
	v_mul_f32_e32 v252, v60, v65
	v_mul_f32_e32 v253, v60, v64
	v_fma_f32 v252, v62, v64, -v252
	v_fma_f32 v253, v62, v65, v253
	v_add_f32_e32 v64, v237, v252
	v_add_f32_e32 v65, v159, v253
	v_cvt_pk_bf16_f32 v203, v64, v65
	ds_write_b32 v104, v203 offset:272
	v_mul_f32_e32 v252, v60, v65
	v_mul_f32_e32 v253, v60, v64
	v_fma_f32 v252, v62, v64, -v252
	v_fma_f32 v253, v62, v65, v253
	v_add_f32_e32 v64, v238, v252
	v_add_f32_e32 v65, v160, v253
	v_cvt_pk_bf16_f32 v202, v64, v65
	ds_write_b32 v104, v202 offset:544
	v_mul_f32_e32 v252, v60, v65
	v_mul_f32_e32 v253, v60, v64
	v_fma_f32 v252, v62, v64, -v252
	v_fma_f32 v253, v62, v65, v253
	v_add_f32_e32 v64, v239, v252
	v_add_f32_e32 v65, v161, v253
	v_cvt_pk_bf16_f32 v203, v64, v65
	ds_write_b32 v104, v203 offset:816
	s_waitcnt lgkmcnt(6)
	v_mul_f32_e32 v252, v60, v65
	v_mul_f32_e32 v253, v60, v64
	v_fma_f32 v252, v62, v64, -v252
	v_fma_f32 v253, v62, v65, v253
	v_add_f32_e32 v64, v240, v252
	v_add_f32_e32 v65, v162, v253
	v_cvt_pk_bf16_f32 v202, v64, v65
	ds_write_b32 v104, v202 offset:1088
	v_mul_f32_e32 v252, v60, v65
	v_mul_f32_e32 v253, v60, v64
	v_fma_f32 v252, v62, v64, -v252
	v_fma_f32 v253, v62, v65, v253
	v_add_f32_e32 v64, v241, v252
	v_add_f32_e32 v65, v163, v253
	v_cvt_pk_bf16_f32 v203, v64, v65
	ds_write_b32 v104, v203 offset:1360
	v_mul_f32_e32 v252, v60, v65
	v_mul_f32_e32 v253, v60, v64
	v_fma_f32 v252, v62, v64, -v252
	v_fma_f32 v253, v62, v65, v253
	v_add_f32_e32 v64, v242, v252
	v_add_f32_e32 v65, v164, v253
	v_cvt_pk_bf16_f32 v202, v64, v65
	ds_write_b32 v104, v202 offset:1632
	v_mul_f32_e32 v252, v60, v65
	v_mul_f32_e32 v253, v60, v64
	v_fma_f32 v252, v62, v64, -v252
	v_fma_f32 v253, v62, v65, v253
	v_add_f32_e32 v64, v243, v252
	v_add_f32_e32 v65, v165, v253
	v_cvt_pk_bf16_f32 v203, v64, v65
	ds_write_b32 v104, v203 offset:1904
	s_waitcnt lgkmcnt(9)
	v_mul_f32_e32 v252, v60, v65
	v_mul_f32_e32 v253, v60, v64
	v_fma_f32 v252, v62, v64, -v252
	v_fma_f32 v253, v62, v65, v253
	v_add_f32_e32 v64, v244, v252
	v_add_f32_e32 v65, v166, v253
	v_cvt_pk_bf16_f32 v202, v64, v65
	ds_write_b32 v104, v202 offset:2176
	v_mul_f32_e32 v252, v60, v65
	v_mul_f32_e32 v253, v60, v64
	v_fma_f32 v252, v62, v64, -v252
	v_fma_f32 v253, v62, v65, v253
	v_add_f32_e32 v64, v245, v252
	v_add_f32_e32 v65, v167, v253
	v_cvt_pk_bf16_f32 v203, v64, v65
	ds_write_b32 v104, v203 offset:2448
	v_mul_f32_e32 v252, v60, v65
	v_mul_f32_e32 v253, v60, v64
	v_fma_f32 v252, v62, v64, -v252
	v_fma_f32 v253, v62, v65, v253
	v_add_f32_e32 v64, v246, v252
	v_add_f32_e32 v65, v168, v253
	v_cvt_pk_bf16_f32 v202, v64, v65
	ds_write_b32 v104, v202 offset:2720
	v_mul_f32_e32 v252, v60, v65
	v_mul_f32_e32 v253, v60, v64
	v_fma_f32 v252, v62, v64, -v252
	v_fma_f32 v253, v62, v65, v253
	v_add_f32_e32 v64, v247, v252
	v_add_f32_e32 v65, v169, v253
	v_cvt_pk_bf16_f32 v203, v64, v65
	ds_write_b32 v104, v203 offset:2992
	s_waitcnt lgkmcnt(12)
	v_mul_f32_e32 v252, v60, v65
	v_mul_f32_e32 v253, v60, v64
	v_fma_f32 v252, v62, v64, -v252
	v_fma_f32 v253, v62, v65, v253
	v_add_f32_e32 v64, v248, v252
	v_add_f32_e32 v65, v170, v253
	v_cvt_pk_bf16_f32 v202, v64, v65
	ds_write_b32 v104, v202 offset:3264
	v_mul_f32_e32 v252, v60, v65
	v_mul_f32_e32 v253, v60, v64
	v_fma_f32 v252, v62, v64, -v252
	v_fma_f32 v253, v62, v65, v253
	v_add_f32_e32 v64, v249, v252
	v_add_f32_e32 v65, v171, v253
	v_cvt_pk_bf16_f32 v203, v64, v65
	ds_write_b32 v104, v203 offset:3536
	v_mul_f32_e32 v252, v60, v65
	v_mul_f32_e32 v253, v60, v64
	v_fma_f32 v252, v62, v64, -v252
	v_fma_f32 v253, v62, v65, v253
	v_add_f32_e32 v64, v250, v252
	v_add_f32_e32 v65, v172, v253
	v_cvt_pk_bf16_f32 v202, v64, v65
	ds_write_b32 v104, v202 offset:3808
	v_mul_f32_e32 v252, v60, v65
	v_mul_f32_e32 v253, v60, v64
	v_fma_f32 v252, v62, v64, -v252
	v_fma_f32 v253, v62, v65, v253
	v_add_f32_e32 v64, v251, v252
	v_add_f32_e32 v65, v173, v253
	v_cvt_pk_bf16_f32 v203, v64, v65
	ds_write_b32 v104, v203 offset:4080
	s_cmp_gt_i32 s34, 0
	s_cselect_b64 s[2:3], -1, 0
	s_or_b64 s[2:3], s[0:1], s[2:3]
	s_and_b64 vcc, exec, s[2:3]
	s_waitcnt lgkmcnt(0)
	ds_read_b128 v[20:23], v99 offset:9216
	ds_read_b128 v[108:111], v99 offset:9280
	s_waitcnt lgkmcnt(1)
	v_mfma_f32_16x16x32_bf16 v[20:23], v[0:3], v[20:23], 0
	s_waitcnt lgkmcnt(0)
	v_mfma_f32_16x16x32_bf16 v[20:23], v[4:7], v[108:111], v[20:23]
	ds_read_b128 v[108:111], v99 offset:9344
	ds_read_b128 v[112:115], v99 offset:9408
	s_waitcnt lgkmcnt(1)
	v_mfma_f32_16x16x32_bf16 v[20:23], v[8:11], v[108:111], v[20:23]
	s_waitcnt lgkmcnt(0)
	v_mfma_f32_16x16x32_bf16 v[20:23], v[12:15], v[112:115], v[20:23]
	s_cbranch_vccz .LBB0_917
	v_lshlrev_b32_e32 v108, 16, v93
	v_and_b32_e32 v109, 0xffff0000, v93
	s_nop 4
	v_pk_fma_f32 v[22:23], v[18:19], v[108:109], v[22:23]
	s_add_i32 s2, s35, -16
	v_mul_f32_e32 v93, 0x3d372713, v23
	v_mul_f32_e32 v93, v23, v93
	v_fma_f32 v93, v23, v93, v23
	v_mul_f32_e32 v93, 0x3fcc422a, v93
	v_mul_f32_e32 v93, 0xbfb8aa3b, v93
	v_exp_f32_e32 v93, v93
	s_cmp_lg_u32 s34, 0
	s_cselect_b32 s2, s2, 0x8000
	v_add_f32_e32 v93, 1.0, v93
	v_rcp_f32_e32 v109, v93
	v_mul_f32_e32 v93, 0x3d372713, v22
	v_mul_f32_e32 v93, v22, v93
	v_fma_f32 v93, v22, v93, v22
	v_mul_f32_e32 v93, 0x3fcc422a, v93
	v_mul_f32_e32 v93, 0xbfb8aa3b, v93
	v_exp_f32_e32 v93, v93
	s_nop 0
	v_add_f32_e32 v93, 1.0, v93
	v_rcp_f32_e32 v108, v93
	s_nop 0
	v_pk_mul_f32 v[22:23], v[22:23], v[108:109]
	v_lshlrev_b32_e32 v108, 16, v92
	v_and_b32_e32 v109, 0xffff0000, v92
	v_pk_fma_f32 v[20:21], v[16:17], v[108:109], v[20:21]
	s_nop 0
	v_mul_f32_e32 v92, 0x3d372713, v21
	v_mul_f32_e32 v92, v21, v92
	v_fma_f32 v92, v21, v92, v21
	v_mul_f32_e32 v92, 0x3fcc422a, v92
	v_mul_f32_e32 v92, 0xbfb8aa3b, v92
	v_exp_f32_e32 v92, v92
	s_nop 0
	v_add_f32_e32 v92, 1.0, v92
	v_rcp_f32_e32 v93, v92
	v_mul_f32_e32 v92, 0x3d372713, v20
	v_mul_f32_e32 v92, v20, v92
	v_fma_f32 v92, v20, v92, v20
	v_mul_f32_e32 v92, 0x3fcc422a, v92
	v_mul_f32_e32 v92, 0xbfb8aa3b, v92
	v_exp_f32_e32 v92, v92
	s_nop 0
	v_add_f32_e32 v92, 1.0, v92
	v_rcp_f32_e32 v92, v92
	s_nop 0
	v_pk_mul_f32 v[20:21], v[20:21], v[92:93]
	v_or_b32_e32 v92, s2, v121
	v_ashrrev_i32_e32 v93, 31, v92
	v_lshlrev_b64 v[92:93], 10, v[92:93]
	v_lshl_add_u64 v[92:93], v[26:27], 0, v[92:93]
	v_cvt_pk_bf16_f32 v20, v20, v21
	v_cvt_pk_bf16_f32 v21, v22, v23
	global_store_dwordx2 v[92:93], v[20:21], off
.LBB0_917:
	v_mfma_f32_16x16x16_bf16 v[204:207], v[28:29], v[90:91], 0
	v_mfma_f32_16x16x16_bf16 v[208:211], v[30:31], v[90:91], 0
	v_mfma_f32_16x16x16_bf16 v[212:215], v[66:67], v[90:91], 0
	v_mfma_f32_16x16x16_bf16 v[216:219], v[68:69], v[90:91], 0
	v_mfma_f32_16x16x16_bf16 v[220:223], v[70:71], v[90:91], 0
	v_mfma_f32_16x16x16_bf16 v[224:227], v[72:73], v[90:91], 0
	v_mfma_f32_16x16x16_bf16 v[228:231], v[74:75], v[90:91], 0
	v_mfma_f32_16x16x16_bf16 v[232:235], v[76:77], v[90:91], 0
	s_nop 7
	ds_write2_b32 v96, v204, v208 offset1:16
	ds_write2_b32 v96, v205, v209 offset0:36 offset1:52
	ds_write2_b32 v96, v206, v210 offset0:72 offset1:88
	ds_write2_b32 v96, v207, v211 offset0:108 offset1:124
	ds_write2_b32 v100, v212, v216 offset0:64 offset1:80
	ds_write2_b32 v100, v213, v217 offset0:100 offset1:116
	ds_write2_b32 v100, v214, v218 offset0:136 offset1:152
	ds_write2_b32 v100, v215, v219 offset0:172 offset1:188
	ds_write2_b32 v101, v220, v224 offset0:128 offset1:144
	ds_write2_b32 v101, v221, v225 offset0:164 offset1:180
	ds_write2_b32 v101, v222, v226 offset0:200 offset1:216
	ds_write2_b32 v101, v223, v227 offset0:236 offset1:252
	ds_write2_b32 v102, v228, v232 offset0:192 offset1:208
	ds_write2_b32 v102, v229, v233 offset0:228 offset1:244
	ds_write2_b32 v103, v230, v234 offset0:8 offset1:24
	ds_write2_b32 v103, v231, v235 offset0:44 offset1:60
	s_waitcnt lgkmcnt(0)
	ds_read_b128 v[236:239], v49
	ds_read_b128 v[240:243], v49 offset:16
	ds_read_b128 v[244:247], v49 offset:32
	ds_read_b128 v[248:251], v49 offset:48
	ds_read_b128 v[158:161], v49 offset:64
	ds_read_b128 v[162:165], v49 offset:80
	ds_read_b128 v[166:169], v49 offset:96
	ds_read_b128 v[170:173], v49 offset:112
	s_waitcnt lgkmcnt(3)
	v_mul_f32_e32 v252, v60, v65
	v_mul_f32_e32 v253, v60, v64
	v_fma_f32 v252, v62, v64, -v252
	v_fma_f32 v253, v62, v65, v253
	v_add_f32_e32 v64, v236, v252
	v_add_f32_e32 v65, v158, v253
	v_cvt_pk_bf16_f32 v202, v64, v65
	ds_write_b32 v104, v202
	v_mul_f32_e32 v252, v60, v65
	v_mul_f32_e32 v253, v60, v64
	v_fma_f32 v252, v62, v64, -v252
	v_fma_f32 v253, v62, v65, v253
	v_add_f32_e32 v64, v237, v252
	v_add_f32_e32 v65, v159, v253
	v_cvt_pk_bf16_f32 v203, v64, v65
	ds_write_b32 v104, v203 offset:272
	v_mul_f32_e32 v252, v60, v65
	v_mul_f32_e32 v253, v60, v64
	v_fma_f32 v252, v62, v64, -v252
	v_fma_f32 v253, v62, v65, v253
	v_add_f32_e32 v64, v238, v252
	v_add_f32_e32 v65, v160, v253
	v_cvt_pk_bf16_f32 v202, v64, v65
	ds_write_b32 v104, v202 offset:544
	v_mul_f32_e32 v252, v60, v65
	v_mul_f32_e32 v253, v60, v64
	v_fma_f32 v252, v62, v64, -v252
	v_fma_f32 v253, v62, v65, v253
	v_add_f32_e32 v64, v239, v252
	v_add_f32_e32 v65, v161, v253
	v_cvt_pk_bf16_f32 v203, v64, v65
	ds_write_b32 v104, v203 offset:816
	s_waitcnt lgkmcnt(6)
	v_mul_f32_e32 v252, v60, v65
	v_mul_f32_e32 v253, v60, v64
	v_fma_f32 v252, v62, v64, -v252
	v_fma_f32 v253, v62, v65, v253
	v_add_f32_e32 v64, v240, v252
	v_add_f32_e32 v65, v162, v253
	v_cvt_pk_bf16_f32 v202, v64, v65
	ds_write_b32 v104, v202 offset:1088
	v_mul_f32_e32 v252, v60, v65
	v_mul_f32_e32 v253, v60, v64
	v_fma_f32 v252, v62, v64, -v252
	v_fma_f32 v253, v62, v65, v253
	v_add_f32_e32 v64, v241, v252
	v_add_f32_e32 v65, v163, v253
	v_cvt_pk_bf16_f32 v203, v64, v65
	ds_write_b32 v104, v203 offset:1360
	v_mul_f32_e32 v252, v60, v65
	v_mul_f32_e32 v253, v60, v64
	v_fma_f32 v252, v62, v64, -v252
	v_fma_f32 v253, v62, v65, v253
	v_add_f32_e32 v64, v242, v252
	v_add_f32_e32 v65, v164, v253
	v_cvt_pk_bf16_f32 v202, v64, v65
	ds_write_b32 v104, v202 offset:1632
	v_mul_f32_e32 v252, v60, v65
	v_mul_f32_e32 v253, v60, v64
	v_fma_f32 v252, v62, v64, -v252
	v_fma_f32 v253, v62, v65, v253
	v_add_f32_e32 v64, v243, v252
	v_add_f32_e32 v65, v165, v253
	v_cvt_pk_bf16_f32 v203, v64, v65
	ds_write_b32 v104, v203 offset:1904
	s_waitcnt lgkmcnt(9)
	v_mul_f32_e32 v252, v60, v65
	v_mul_f32_e32 v253, v60, v64
	v_fma_f32 v252, v62, v64, -v252
	v_fma_f32 v253, v62, v65, v253
	v_add_f32_e32 v64, v244, v252
	v_add_f32_e32 v65, v166, v253
	v_cvt_pk_bf16_f32 v202, v64, v65
	ds_write_b32 v104, v202 offset:2176
	v_mul_f32_e32 v252, v60, v65
	v_mul_f32_e32 v253, v60, v64
	v_fma_f32 v252, v62, v64, -v252
	v_fma_f32 v253, v62, v65, v253
	v_add_f32_e32 v64, v245, v252
	v_add_f32_e32 v65, v167, v253
	v_cvt_pk_bf16_f32 v203, v64, v65
	ds_write_b32 v104, v203 offset:2448
	v_mul_f32_e32 v252, v60, v65
	v_mul_f32_e32 v253, v60, v64
	v_fma_f32 v252, v62, v64, -v252
	v_fma_f32 v253, v62, v65, v253
	v_add_f32_e32 v64, v246, v252
	v_add_f32_e32 v65, v168, v253
	v_cvt_pk_bf16_f32 v202, v64, v65
	ds_write_b32 v104, v202 offset:2720
	v_mul_f32_e32 v252, v60, v65
	v_mul_f32_e32 v253, v60, v64
	v_fma_f32 v252, v62, v64, -v252
	v_fma_f32 v253, v62, v65, v253
	v_add_f32_e32 v64, v247, v252
	v_add_f32_e32 v65, v169, v253
	v_cvt_pk_bf16_f32 v203, v64, v65
	ds_write_b32 v104, v203 offset:2992
	s_waitcnt lgkmcnt(12)
	v_mul_f32_e32 v252, v60, v65
	v_mul_f32_e32 v253, v60, v64
	v_fma_f32 v252, v62, v64, -v252
	v_fma_f32 v253, v62, v65, v253
	v_add_f32_e32 v64, v248, v252
	v_add_f32_e32 v65, v170, v253
	v_cvt_pk_bf16_f32 v202, v64, v65
	ds_write_b32 v104, v202 offset:3264
	v_mul_f32_e32 v252, v60, v65
	v_mul_f32_e32 v253, v60, v64
	v_fma_f32 v252, v62, v64, -v252
	v_fma_f32 v253, v62, v65, v253
	v_add_f32_e32 v64, v249, v252
	v_add_f32_e32 v65, v171, v253
	v_cvt_pk_bf16_f32 v203, v64, v65
	ds_write_b32 v104, v203 offset:3536
	v_mul_f32_e32 v252, v60, v65
	v_mul_f32_e32 v253, v60, v64
	v_fma_f32 v252, v62, v64, -v252
	v_fma_f32 v253, v62, v65, v253
	v_add_f32_e32 v64, v250, v252
	v_add_f32_e32 v65, v172, v253
	v_cvt_pk_bf16_f32 v202, v64, v65
	ds_write_b32 v104, v202 offset:3808
	v_mul_f32_e32 v252, v60, v65
	v_mul_f32_e32 v253, v60, v64
	v_fma_f32 v252, v62, v64, -v252
	v_fma_f32 v253, v62, v65, v253
	v_add_f32_e32 v64, v251, v252
	v_add_f32_e32 v65, v173, v253
	v_cvt_pk_bf16_f32 v203, v64, v65
	ds_write_b32 v104, v203 offset:4080
	s_cmp_lt_i32 s34, 0
	s_cselect_b64 s[4:5], -1, 0
	s_xor_b64 s[2:3], s[0:1], -1
	s_and_b64 s[4:5], s[2:3], s[4:5]
	s_and_b64 vcc, exec, s[4:5]
	s_waitcnt lgkmcnt(0)
	ds_read_b128 v[20:23], v99 offset:9216
	ds_read_b128 v[108:111], v99 offset:9280
	s_waitcnt lgkmcnt(1)
	v_mfma_f32_16x16x32_bf16 v[20:23], v[0:3], v[20:23], 0
	s_waitcnt lgkmcnt(0)
	v_mfma_f32_16x16x32_bf16 v[20:23], v[4:7], v[108:111], v[20:23]
	ds_read_b128 v[108:111], v99 offset:9344
	ds_read_b128 v[112:115], v99 offset:9408
	s_waitcnt lgkmcnt(1)
	v_mfma_f32_16x16x32_bf16 v[20:23], v[8:11], v[108:111], v[20:23]
	s_waitcnt lgkmcnt(0)
	v_mfma_f32_16x16x32_bf16 v[20:23], v[12:15], v[112:115], v[20:23]
	s_cbranch_vccnz .LBB0_919
	v_lshlrev_b32_e32 v92, 16, v91
	v_and_b32_e32 v93, 0xffff0000, v91
	s_nop 4
	v_pk_fma_f32 v[22:23], v[18:19], v[92:93], v[22:23]
	s_cmp_lg_u32 s34, -1
	v_mul_f32_e32 v91, 0x3d372713, v23
	v_mul_f32_e32 v91, v23, v91
	v_fma_f32 v91, v23, v91, v23
	v_mul_f32_e32 v91, 0x3fcc422a, v91
	v_mul_f32_e32 v91, 0xbfb8aa3b, v91
	v_exp_f32_e32 v91, v91
	s_cselect_b32 s4, s35, 0x8000
	v_add_f32_e32 v91, 1.0, v91
	v_rcp_f32_e32 v93, v91
	v_mul_f32_e32 v91, 0x3d372713, v22
	v_mul_f32_e32 v91, v22, v91
	v_fma_f32 v91, v22, v91, v22
	v_mul_f32_e32 v91, 0x3fcc422a, v91
	v_mul_f32_e32 v91, 0xbfb8aa3b, v91
	v_exp_f32_e32 v91, v91
	s_nop 0
	v_add_f32_e32 v91, 1.0, v91
	v_rcp_f32_e32 v92, v91
	s_nop 0
	v_pk_mul_f32 v[22:23], v[22:23], v[92:93]
	v_lshlrev_b32_e32 v92, 16, v90
	v_and_b32_e32 v93, 0xffff0000, v90
	v_pk_fma_f32 v[20:21], v[16:17], v[92:93], v[20:21]
	s_nop 0
	v_mul_f32_e32 v90, 0x3d372713, v21
	v_mul_f32_e32 v90, v21, v90
	v_fma_f32 v90, v21, v90, v21
	v_mul_f32_e32 v90, 0x3fcc422a, v90
	v_mul_f32_e32 v90, 0xbfb8aa3b, v90
	v_exp_f32_e32 v90, v90
	s_nop 0
	v_add_f32_e32 v90, 1.0, v90
	v_rcp_f32_e32 v91, v90
	v_mul_f32_e32 v90, 0x3d372713, v20
	v_mul_f32_e32 v90, v20, v90
	v_fma_f32 v90, v20, v90, v20
	v_mul_f32_e32 v90, 0x3fcc422a, v90
	v_mul_f32_e32 v90, 0xbfb8aa3b, v90
	v_exp_f32_e32 v90, v90
	s_nop 0
	v_add_f32_e32 v90, 1.0, v90
	v_rcp_f32_e32 v90, v90
	s_nop 0
	v_pk_mul_f32 v[20:21], v[20:21], v[90:91]
	v_or_b32_e32 v90, s4, v121
	v_ashrrev_i32_e32 v91, 31, v90
	v_lshlrev_b64 v[90:91], 10, v[90:91]
	v_lshl_add_u64 v[90:91], v[26:27], 0, v[90:91]
	v_cvt_pk_bf16_f32 v20, v20, v21
	v_cvt_pk_bf16_f32 v21, v22, v23
	global_store_dwordx2 v[90:91], v[20:21], off
.LBB0_919:
	v_mfma_f32_16x16x16_bf16 v[204:207], v[28:29], v[88:89], 0
	v_mfma_f32_16x16x16_bf16 v[208:211], v[30:31], v[88:89], 0
	v_mfma_f32_16x16x16_bf16 v[212:215], v[66:67], v[88:89], 0
	v_mfma_f32_16x16x16_bf16 v[216:219], v[68:69], v[88:89], 0
	v_mfma_f32_16x16x16_bf16 v[220:223], v[70:71], v[88:89], 0
	v_mfma_f32_16x16x16_bf16 v[224:227], v[72:73], v[88:89], 0
	v_mfma_f32_16x16x16_bf16 v[228:231], v[74:75], v[88:89], 0
	v_mfma_f32_16x16x16_bf16 v[232:235], v[76:77], v[88:89], 0
	s_nop 7
	ds_write2_b32 v96, v204, v208 offset1:16
	ds_write2_b32 v96, v205, v209 offset0:36 offset1:52
	ds_write2_b32 v96, v206, v210 offset0:72 offset1:88
	ds_write2_b32 v96, v207, v211 offset0:108 offset1:124
	ds_write2_b32 v100, v212, v216 offset0:64 offset1:80
	ds_write2_b32 v100, v213, v217 offset0:100 offset1:116
	ds_write2_b32 v100, v214, v218 offset0:136 offset1:152
	ds_write2_b32 v100, v215, v219 offset0:172 offset1:188
	ds_write2_b32 v101, v220, v224 offset0:128 offset1:144
	ds_write2_b32 v101, v221, v225 offset0:164 offset1:180
	ds_write2_b32 v101, v222, v226 offset0:200 offset1:216
	ds_write2_b32 v101, v223, v227 offset0:236 offset1:252
	ds_write2_b32 v102, v228, v232 offset0:192 offset1:208
	ds_write2_b32 v102, v229, v233 offset0:228 offset1:244
	ds_write2_b32 v103, v230, v234 offset0:8 offset1:24
	ds_write2_b32 v103, v231, v235 offset0:44 offset1:60
	s_waitcnt lgkmcnt(0)
	ds_read_b128 v[236:239], v49
	ds_read_b128 v[240:243], v49 offset:16
	ds_read_b128 v[244:247], v49 offset:32
	ds_read_b128 v[248:251], v49 offset:48
	ds_read_b128 v[158:161], v49 offset:64
	ds_read_b128 v[162:165], v49 offset:80
	ds_read_b128 v[166:169], v49 offset:96
	ds_read_b128 v[170:173], v49 offset:112
	s_waitcnt lgkmcnt(3)
	v_mul_f32_e32 v252, v60, v65
	v_mul_f32_e32 v253, v60, v64
	v_fma_f32 v252, v62, v64, -v252
	v_fma_f32 v253, v62, v65, v253
	v_add_f32_e32 v64, v236, v252
	v_add_f32_e32 v65, v158, v253
	v_cvt_pk_bf16_f32 v202, v64, v65
	ds_write_b32 v104, v202
	v_mul_f32_e32 v252, v60, v65
	v_mul_f32_e32 v253, v60, v64
	v_fma_f32 v252, v62, v64, -v252
	v_fma_f32 v253, v62, v65, v253
	v_add_f32_e32 v64, v237, v252
	v_add_f32_e32 v65, v159, v253
	v_cvt_pk_bf16_f32 v203, v64, v65
	ds_write_b32 v104, v203 offset:272
	v_mul_f32_e32 v252, v60, v65
	v_mul_f32_e32 v253, v60, v64
	v_fma_f32 v252, v62, v64, -v252
	v_fma_f32 v253, v62, v65, v253
	v_add_f32_e32 v64, v238, v252
	v_add_f32_e32 v65, v160, v253
	v_cvt_pk_bf16_f32 v202, v64, v65
	ds_write_b32 v104, v202 offset:544
	v_mul_f32_e32 v252, v60, v65
	v_mul_f32_e32 v253, v60, v64
	v_fma_f32 v252, v62, v64, -v252
	v_fma_f32 v253, v62, v65, v253
	v_add_f32_e32 v64, v239, v252
	v_add_f32_e32 v65, v161, v253
	v_cvt_pk_bf16_f32 v203, v64, v65
	ds_write_b32 v104, v203 offset:816
	s_waitcnt lgkmcnt(6)
	v_mul_f32_e32 v252, v60, v65
	v_mul_f32_e32 v253, v60, v64
	v_fma_f32 v252, v62, v64, -v252
	v_fma_f32 v253, v62, v65, v253
	v_add_f32_e32 v64, v240, v252
	v_add_f32_e32 v65, v162, v253
	v_cvt_pk_bf16_f32 v202, v64, v65
	ds_write_b32 v104, v202 offset:1088
	v_mul_f32_e32 v252, v60, v65
	v_mul_f32_e32 v253, v60, v64
	v_fma_f32 v252, v62, v64, -v252
	v_fma_f32 v253, v62, v65, v253
	v_add_f32_e32 v64, v241, v252
	v_add_f32_e32 v65, v163, v253
	v_cvt_pk_bf16_f32 v203, v64, v65
	ds_write_b32 v104, v203 offset:1360
	v_mul_f32_e32 v252, v60, v65
	v_mul_f32_e32 v253, v60, v64
	v_fma_f32 v252, v62, v64, -v252
	v_fma_f32 v253, v62, v65, v253
	v_add_f32_e32 v64, v242, v252
	v_add_f32_e32 v65, v164, v253
	v_cvt_pk_bf16_f32 v202, v64, v65
	ds_write_b32 v104, v202 offset:1632
	v_mul_f32_e32 v252, v60, v65
	v_mul_f32_e32 v253, v60, v64
	v_fma_f32 v252, v62, v64, -v252
	v_fma_f32 v253, v62, v65, v253
	v_add_f32_e32 v64, v243, v252
	v_add_f32_e32 v65, v165, v253
	v_cvt_pk_bf16_f32 v203, v64, v65
	ds_write_b32 v104, v203 offset:1904
	s_waitcnt lgkmcnt(9)
	v_mul_f32_e32 v252, v60, v65
	v_mul_f32_e32 v253, v60, v64
	v_fma_f32 v252, v62, v64, -v252
	v_fma_f32 v253, v62, v65, v253
	v_add_f32_e32 v64, v244, v252
	v_add_f32_e32 v65, v166, v253
	v_cvt_pk_bf16_f32 v202, v64, v65
	ds_write_b32 v104, v202 offset:2176
	v_mul_f32_e32 v252, v60, v65
	v_mul_f32_e32 v253, v60, v64
	v_fma_f32 v252, v62, v64, -v252
	v_fma_f32 v253, v62, v65, v253
	v_add_f32_e32 v64, v245, v252
	v_add_f32_e32 v65, v167, v253
	v_cvt_pk_bf16_f32 v203, v64, v65
	ds_write_b32 v104, v203 offset:2448
	v_mul_f32_e32 v252, v60, v65
	v_mul_f32_e32 v253, v60, v64
	v_fma_f32 v252, v62, v64, -v252
	v_fma_f32 v253, v62, v65, v253
	v_add_f32_e32 v64, v246, v252
	v_add_f32_e32 v65, v168, v253
	v_cvt_pk_bf16_f32 v202, v64, v65
	ds_write_b32 v104, v202 offset:2720
	v_mul_f32_e32 v252, v60, v65
	v_mul_f32_e32 v253, v60, v64
	v_fma_f32 v252, v62, v64, -v252
	v_fma_f32 v253, v62, v65, v253
	v_add_f32_e32 v64, v247, v252
	v_add_f32_e32 v65, v169, v253
	v_cvt_pk_bf16_f32 v203, v64, v65
	ds_write_b32 v104, v203 offset:2992
	s_waitcnt lgkmcnt(12)
	v_mul_f32_e32 v252, v60, v65
	v_mul_f32_e32 v253, v60, v64
	v_fma_f32 v252, v62, v64, -v252
	v_fma_f32 v253, v62, v65, v253
	v_add_f32_e32 v64, v248, v252
	v_add_f32_e32 v65, v170, v253
	v_cvt_pk_bf16_f32 v202, v64, v65
	ds_write_b32 v104, v202 offset:3264
	v_mul_f32_e32 v252, v60, v65
	v_mul_f32_e32 v253, v60, v64
	v_fma_f32 v252, v62, v64, -v252
	v_fma_f32 v253, v62, v65, v253
	v_add_f32_e32 v64, v249, v252
	v_add_f32_e32 v65, v171, v253
	v_cvt_pk_bf16_f32 v203, v64, v65
	ds_write_b32 v104, v203 offset:3536
	v_mul_f32_e32 v252, v60, v65
	v_mul_f32_e32 v253, v60, v64
	v_fma_f32 v252, v62, v64, -v252
	v_fma_f32 v253, v62, v65, v253
	v_add_f32_e32 v64, v250, v252
	v_add_f32_e32 v65, v172, v253
	v_cvt_pk_bf16_f32 v202, v64, v65
	ds_write_b32 v104, v202 offset:3808
	v_mul_f32_e32 v252, v60, v65
	v_mul_f32_e32 v253, v60, v64
	v_fma_f32 v252, v62, v64, -v252
	v_fma_f32 v253, v62, v65, v253
	v_add_f32_e32 v64, v251, v252
	v_add_f32_e32 v65, v173, v253
	v_cvt_pk_bf16_f32 v203, v64, v65
	ds_write_b32 v104, v203 offset:4080
	s_cmp_lt_i32 s34, -1
	s_cselect_b64 s[4:5], -1, 0
	s_and_b64 s[4:5], s[2:3], s[4:5]
	s_and_b64 vcc, exec, s[4:5]
	s_waitcnt lgkmcnt(0)
	ds_read_b128 v[20:23], v99 offset:9216
	ds_read_b128 v[90:93], v99 offset:9280
	s_waitcnt lgkmcnt(1)
	v_mfma_f32_16x16x32_bf16 v[20:23], v[0:3], v[20:23], 0
	s_waitcnt lgkmcnt(0)
	v_mfma_f32_16x16x32_bf16 v[20:23], v[4:7], v[90:93], v[20:23]
	ds_read_b128 v[90:93], v99 offset:9344
	ds_read_b128 v[108:111], v99 offset:9408
	s_waitcnt lgkmcnt(1)
	v_mfma_f32_16x16x32_bf16 v[20:23], v[8:11], v[90:93], v[20:23]
	s_waitcnt lgkmcnt(0)
	v_mfma_f32_16x16x32_bf16 v[20:23], v[12:15], v[108:111], v[20:23]
	s_cbranch_vccnz .LBB0_921
	v_lshlrev_b32_e32 v90, 16, v89
	v_and_b32_e32 v91, 0xffff0000, v89
	s_nop 4
	v_pk_fma_f32 v[22:23], v[18:19], v[90:91], v[22:23]
	s_add_i32 s4, s35, 16
	v_mul_f32_e32 v89, 0x3d372713, v23
	v_mul_f32_e32 v89, v23, v89
	v_fma_f32 v89, v23, v89, v23
	v_mul_f32_e32 v89, 0x3fcc422a, v89
	v_mul_f32_e32 v89, 0xbfb8aa3b, v89
	v_exp_f32_e32 v89, v89
	s_cmp_lg_u32 s34, -2
	s_cselect_b32 s4, s4, 0x8000
	v_add_f32_e32 v89, 1.0, v89
	v_rcp_f32_e32 v91, v89
	v_mul_f32_e32 v89, 0x3d372713, v22
	v_mul_f32_e32 v89, v22, v89
	v_fma_f32 v89, v22, v89, v22
	v_mul_f32_e32 v89, 0x3fcc422a, v89
	v_mul_f32_e32 v89, 0xbfb8aa3b, v89
	v_exp_f32_e32 v89, v89
	s_nop 0
	v_add_f32_e32 v89, 1.0, v89
	v_rcp_f32_e32 v90, v89
	s_nop 0
	v_pk_mul_f32 v[22:23], v[22:23], v[90:91]
	v_lshlrev_b32_e32 v90, 16, v88
	v_and_b32_e32 v91, 0xffff0000, v88
	v_pk_fma_f32 v[20:21], v[16:17], v[90:91], v[20:21]
	s_nop 0
	v_mul_f32_e32 v88, 0x3d372713, v21
	v_mul_f32_e32 v88, v21, v88
	v_fma_f32 v88, v21, v88, v21
	v_mul_f32_e32 v88, 0x3fcc422a, v88
	v_mul_f32_e32 v88, 0xbfb8aa3b, v88
	v_exp_f32_e32 v88, v88
	s_nop 0
	v_add_f32_e32 v88, 1.0, v88
	v_rcp_f32_e32 v89, v88
	v_mul_f32_e32 v88, 0x3d372713, v20
	v_mul_f32_e32 v88, v20, v88
	v_fma_f32 v88, v20, v88, v20
	v_mul_f32_e32 v88, 0x3fcc422a, v88
	v_mul_f32_e32 v88, 0xbfb8aa3b, v88
	v_exp_f32_e32 v88, v88
	s_nop 0
	v_add_f32_e32 v88, 1.0, v88
	v_rcp_f32_e32 v88, v88
	s_nop 0
	v_pk_mul_f32 v[20:21], v[20:21], v[88:89]
	v_or_b32_e32 v88, s4, v121
	v_ashrrev_i32_e32 v89, 31, v88
	v_lshlrev_b64 v[88:89], 10, v[88:89]
	v_lshl_add_u64 v[88:89], v[26:27], 0, v[88:89]
	v_cvt_pk_bf16_f32 v20, v20, v21
	v_cvt_pk_bf16_f32 v21, v22, v23
	global_store_dwordx2 v[88:89], v[20:21], off
.LBB0_921:
	v_mfma_f32_16x16x16_bf16 v[204:207], v[28:29], v[78:79], 0
	v_mfma_f32_16x16x16_bf16 v[208:211], v[30:31], v[78:79], 0
	v_mfma_f32_16x16x16_bf16 v[212:215], v[66:67], v[78:79], 0
	v_mfma_f32_16x16x16_bf16 v[216:219], v[68:69], v[78:79], 0
	v_mfma_f32_16x16x16_bf16 v[220:223], v[70:71], v[78:79], 0
	v_mfma_f32_16x16x16_bf16 v[224:227], v[72:73], v[78:79], 0
	v_mfma_f32_16x16x16_bf16 v[228:231], v[74:75], v[78:79], 0
	v_mfma_f32_16x16x16_bf16 v[232:235], v[76:77], v[78:79], 0
	s_nop 7
	ds_write2_b32 v96, v204, v208 offset1:16
	ds_write2_b32 v96, v205, v209 offset0:36 offset1:52
	ds_write2_b32 v96, v206, v210 offset0:72 offset1:88
	ds_write2_b32 v96, v207, v211 offset0:108 offset1:124
	ds_write2_b32 v100, v212, v216 offset0:64 offset1:80
	ds_write2_b32 v100, v213, v217 offset0:100 offset1:116
	ds_write2_b32 v100, v214, v218 offset0:136 offset1:152
	ds_write2_b32 v100, v215, v219 offset0:172 offset1:188
	ds_write2_b32 v101, v220, v224 offset0:128 offset1:144
	ds_write2_b32 v101, v221, v225 offset0:164 offset1:180
	ds_write2_b32 v101, v222, v226 offset0:200 offset1:216
	ds_write2_b32 v101, v223, v227 offset0:236 offset1:252
	ds_write2_b32 v102, v228, v232 offset0:192 offset1:208
	ds_write2_b32 v102, v229, v233 offset0:228 offset1:244
	ds_write2_b32 v103, v230, v234 offset0:8 offset1:24
	ds_write2_b32 v103, v231, v235 offset0:44 offset1:60
	s_waitcnt lgkmcnt(0)
	ds_read_b128 v[236:239], v49
	ds_read_b128 v[240:243], v49 offset:16
	ds_read_b128 v[244:247], v49 offset:32
	ds_read_b128 v[248:251], v49 offset:48
	ds_read_b128 v[158:161], v49 offset:64
	ds_read_b128 v[162:165], v49 offset:80
	ds_read_b128 v[166:169], v49 offset:96
	ds_read_b128 v[170:173], v49 offset:112
	s_waitcnt lgkmcnt(3)
	v_mul_f32_e32 v252, v60, v65
	v_mul_f32_e32 v253, v60, v64
	v_fma_f32 v252, v62, v64, -v252
	v_fma_f32 v253, v62, v65, v253
	v_add_f32_e32 v64, v236, v252
	v_add_f32_e32 v65, v158, v253
	v_cvt_pk_bf16_f32 v202, v64, v65
	ds_write_b32 v104, v202
	v_mul_f32_e32 v252, v60, v65
	v_mul_f32_e32 v253, v60, v64
	v_fma_f32 v252, v62, v64, -v252
	v_fma_f32 v253, v62, v65, v253
	v_add_f32_e32 v64, v237, v252
	v_add_f32_e32 v65, v159, v253
	v_cvt_pk_bf16_f32 v203, v64, v65
	ds_write_b32 v104, v203 offset:272
	v_mul_f32_e32 v252, v60, v65
	v_mul_f32_e32 v253, v60, v64
	v_fma_f32 v252, v62, v64, -v252
	v_fma_f32 v253, v62, v65, v253
	v_add_f32_e32 v64, v238, v252
	v_add_f32_e32 v65, v160, v253
	v_cvt_pk_bf16_f32 v202, v64, v65
	ds_write_b32 v104, v202 offset:544
	v_mul_f32_e32 v252, v60, v65
	v_mul_f32_e32 v253, v60, v64
	v_fma_f32 v252, v62, v64, -v252
	v_fma_f32 v253, v62, v65, v253
	v_add_f32_e32 v64, v239, v252
	v_add_f32_e32 v65, v161, v253
	v_cvt_pk_bf16_f32 v203, v64, v65
	ds_write_b32 v104, v203 offset:816
	s_waitcnt lgkmcnt(6)
	v_mul_f32_e32 v252, v60, v65
	v_mul_f32_e32 v253, v60, v64
	v_fma_f32 v252, v62, v64, -v252
	v_fma_f32 v253, v62, v65, v253
	v_add_f32_e32 v64, v240, v252
	v_add_f32_e32 v65, v162, v253
	v_cvt_pk_bf16_f32 v202, v64, v65
	ds_write_b32 v104, v202 offset:1088
	v_mul_f32_e32 v252, v60, v65
	v_mul_f32_e32 v253, v60, v64
	v_fma_f32 v252, v62, v64, -v252
	v_fma_f32 v253, v62, v65, v253
	v_add_f32_e32 v64, v241, v252
	v_add_f32_e32 v65, v163, v253
	v_cvt_pk_bf16_f32 v203, v64, v65
	ds_write_b32 v104, v203 offset:1360
	v_mul_f32_e32 v252, v60, v65
	v_mul_f32_e32 v253, v60, v64
	v_fma_f32 v252, v62, v64, -v252
	v_fma_f32 v253, v62, v65, v253
	v_add_f32_e32 v64, v242, v252
	v_add_f32_e32 v65, v164, v253
	v_cvt_pk_bf16_f32 v202, v64, v65
	ds_write_b32 v104, v202 offset:1632
	v_mul_f32_e32 v252, v60, v65
	v_mul_f32_e32 v253, v60, v64
	v_fma_f32 v252, v62, v64, -v252
	v_fma_f32 v253, v62, v65, v253
	v_add_f32_e32 v64, v243, v252
	v_add_f32_e32 v65, v165, v253
	v_cvt_pk_bf16_f32 v203, v64, v65
	ds_write_b32 v104, v203 offset:1904
	s_waitcnt lgkmcnt(9)
	v_mul_f32_e32 v252, v60, v65
	v_mul_f32_e32 v253, v60, v64
	v_fma_f32 v252, v62, v64, -v252
	v_fma_f32 v253, v62, v65, v253
	v_add_f32_e32 v64, v244, v252
	v_add_f32_e32 v65, v166, v253
	v_cvt_pk_bf16_f32 v202, v64, v65
	ds_write_b32 v104, v202 offset:2176
	v_mul_f32_e32 v252, v60, v65
	v_mul_f32_e32 v253, v60, v64
	v_fma_f32 v252, v62, v64, -v252
	v_fma_f32 v253, v62, v65, v253
	v_add_f32_e32 v64, v245, v252
	v_add_f32_e32 v65, v167, v253
	v_cvt_pk_bf16_f32 v203, v64, v65
	ds_write_b32 v104, v203 offset:2448
	v_mul_f32_e32 v252, v60, v65
	v_mul_f32_e32 v253, v60, v64
	v_fma_f32 v252, v62, v64, -v252
	v_fma_f32 v253, v62, v65, v253
	v_add_f32_e32 v64, v246, v252
	v_add_f32_e32 v65, v168, v253
	v_cvt_pk_bf16_f32 v202, v64, v65
	ds_write_b32 v104, v202 offset:2720
	v_mul_f32_e32 v252, v60, v65
	v_mul_f32_e32 v253, v60, v64
	v_fma_f32 v252, v62, v64, -v252
	v_fma_f32 v253, v62, v65, v253
	v_add_f32_e32 v64, v247, v252
	v_add_f32_e32 v65, v169, v253
	v_cvt_pk_bf16_f32 v203, v64, v65
	ds_write_b32 v104, v203 offset:2992
	s_waitcnt lgkmcnt(12)
	v_mul_f32_e32 v252, v60, v65
	v_mul_f32_e32 v253, v60, v64
	v_fma_f32 v252, v62, v64, -v252
	v_fma_f32 v253, v62, v65, v253
	v_add_f32_e32 v64, v248, v252
	v_add_f32_e32 v65, v170, v253
	v_cvt_pk_bf16_f32 v202, v64, v65
	ds_write_b32 v104, v202 offset:3264
	v_mul_f32_e32 v252, v60, v65
	v_mul_f32_e32 v253, v60, v64
	v_fma_f32 v252, v62, v64, -v252
	v_fma_f32 v253, v62, v65, v253
	v_add_f32_e32 v64, v249, v252
	v_add_f32_e32 v65, v171, v253
	v_cvt_pk_bf16_f32 v203, v64, v65
	ds_write_b32 v104, v203 offset:3536
	v_mul_f32_e32 v252, v60, v65
	v_mul_f32_e32 v253, v60, v64
	v_fma_f32 v252, v62, v64, -v252
	v_fma_f32 v253, v62, v65, v253
	v_add_f32_e32 v64, v250, v252
	v_add_f32_e32 v65, v172, v253
	v_cvt_pk_bf16_f32 v202, v64, v65
	ds_write_b32 v104, v202 offset:3808
	v_mul_f32_e32 v252, v60, v65
	v_mul_f32_e32 v253, v60, v64
	v_fma_f32 v252, v62, v64, -v252
	v_fma_f32 v253, v62, v65, v253
	v_add_f32_e32 v64, v251, v252
	v_add_f32_e32 v65, v173, v253
	v_cvt_pk_bf16_f32 v203, v64, v65
	ds_write_b32 v104, v203 offset:4080
	s_cmp_lt_i32 s34, -2
	s_cselect_b64 s[4:5], -1, 0
	s_and_b64 s[2:3], s[2:3], s[4:5]
	s_and_b64 vcc, exec, s[2:3]
	s_waitcnt lgkmcnt(0)
	ds_read_b128 v[20:23], v99 offset:9216
	ds_read_b128 v[88:91], v99 offset:9280
	s_waitcnt lgkmcnt(1)
	v_mfma_f32_16x16x32_bf16 v[20:23], v[0:3], v[20:23], 0
	s_waitcnt lgkmcnt(0)
	v_mfma_f32_16x16x32_bf16 v[20:23], v[4:7], v[88:91], v[20:23]
	ds_read_b128 v[88:91], v99 offset:9344
	ds_read_b128 v[108:111], v99 offset:9408
	s_waitcnt lgkmcnt(1)
	v_mfma_f32_16x16x32_bf16 v[20:23], v[8:11], v[88:91], v[20:23]
	s_waitcnt lgkmcnt(0)
	v_mfma_f32_16x16x32_bf16 v[20:23], v[12:15], v[108:111], v[20:23]
	s_cbranch_vccnz .LBB0_914
	v_lshlrev_b32_e32 v88, 16, v79
	v_and_b32_e32 v89, 0xffff0000, v79
	s_nop 4
	v_pk_fma_f32 v[22:23], v[18:19], v[88:89], v[22:23]
	s_add_i32 s2, s35, 32
	v_mul_f32_e32 v79, 0x3d372713, v23
	v_mul_f32_e32 v79, v23, v79
	v_fma_f32 v79, v23, v79, v23
	v_mul_f32_e32 v79, 0x3fcc422a, v79
	v_mul_f32_e32 v79, 0xbfb8aa3b, v79
	v_exp_f32_e32 v79, v79
	s_cmp_lg_u32 s34, -3
	s_cselect_b32 s2, s2, 0x8000
	v_add_f32_e32 v79, 1.0, v79
	v_rcp_f32_e32 v89, v79
	v_mul_f32_e32 v79, 0x3d372713, v22
	v_mul_f32_e32 v79, v22, v79
	v_fma_f32 v79, v22, v79, v22
	v_mul_f32_e32 v79, 0x3fcc422a, v79
	v_mul_f32_e32 v79, 0xbfb8aa3b, v79
	v_exp_f32_e32 v79, v79
	s_nop 0
	v_add_f32_e32 v79, 1.0, v79
	v_rcp_f32_e32 v88, v79
	s_nop 0
	v_pk_mul_f32 v[22:23], v[22:23], v[88:89]
	v_lshlrev_b32_e32 v88, 16, v78
	v_and_b32_e32 v89, 0xffff0000, v78
	v_pk_fma_f32 v[20:21], v[16:17], v[88:89], v[20:21]
	s_nop 0
	v_mul_f32_e32 v78, 0x3d372713, v21
	v_mul_f32_e32 v78, v21, v78
	v_fma_f32 v78, v21, v78, v21
	v_mul_f32_e32 v78, 0x3fcc422a, v78
	v_mul_f32_e32 v78, 0xbfb8aa3b, v78
	v_exp_f32_e32 v78, v78
	s_nop 0
	v_add_f32_e32 v78, 1.0, v78
	v_rcp_f32_e32 v79, v78
	v_mul_f32_e32 v78, 0x3d372713, v20
	v_mul_f32_e32 v78, v20, v78
	v_fma_f32 v78, v20, v78, v20
	v_mul_f32_e32 v78, 0x3fcc422a, v78
	v_mul_f32_e32 v78, 0xbfb8aa3b, v78
	v_exp_f32_e32 v78, v78
	s_nop 0
	v_add_f32_e32 v78, 1.0, v78
	v_rcp_f32_e32 v78, v78
	s_nop 0
	v_pk_mul_f32 v[20:21], v[20:21], v[78:79]
	v_or_b32_e32 v78, s2, v121
	v_ashrrev_i32_e32 v79, 31, v78
	v_lshlrev_b64 v[78:79], 10, v[78:79]
	v_lshl_add_u64 v[78:79], v[26:27], 0, v[78:79]
	v_cvt_pk_bf16_f32 v20, v20, v21
	v_cvt_pk_bf16_f32 v21, v22, v23
	global_store_dwordx2 v[78:79], v[20:21], off
	s_branch .LBB0_914
